# grid barrier: non-leader workgroups wait on the top-level generation word directly (per-XCD generation hop removed)
# speedup vs baseline: 1.0257x; 1.0024x over previous
.LBB0_874:
	s_or_b64 exec, exec, s[8:9]
	v_cvt_f32_u32_e32 v5, v3
	s_waitcnt vmcnt(0)
	v_readfirstlane_b32 s6, v4
	v_sub_u32_e32 v4, 0, v3
	v_rcp_iflag_f32_e32 v5, v5
	v_add_u32_e32 v6, s6, v0
	v_mul_f32_e32 v5, 0x4f7ffffe, v5
	v_cvt_u32_f32_e32 v5, v5
	v_mul_lo_u32 v0, v4, v5
	v_mul_hi_u32 v0, v5, v0
	v_add_u32_e32 v0, v5, v0
	v_mul_hi_u32 v0, v6, v0
	v_mul_lo_u32 v4, v0, v3
	v_sub_u32_e32 v4, v6, v4
	v_add_u32_e32 v5, 1, v0
	v_cmp_ge_u32_e32 vcc, v4, v3
	s_nop 1
	v_cndmask_b32_e32 v0, v0, v5, vcc
	v_sub_u32_e32 v5, v4, v3
	v_cndmask_b32_e32 v4, v4, v5, vcc
	v_add_u32_e32 v5, 1, v0
	v_cmp_ge_u32_e32 vcc, v4, v3
	v_add_u32_e32 v4, 1, v6
	s_nop 0
	v_cndmask_b32_e32 v0, v0, v5, vcc
	v_mul_lo_u32 v5, v3, v0
	v_add_u32_e32 v3, v5, v3
	v_cmp_ne_u32_e32 vcc, v4, v3
	s_and_saveexec_b64 s[6:7], vcc
	s_xor_b64 s[6:7], exec, s[6:7]
	s_cbranch_execz .LBB0_888
	s_waitcnt lgkmcnt(0)
	v_readlane_b32 s10, v252, 51
	v_readlane_b32 s11, v252, 52
	s_nop 4
	global_load_dword v2, v1, s[10:11] sc1
	s_waitcnt vmcnt(0)
	v_cmp_eq_u32_e32 vcc, v2, v0
	s_and_saveexec_b64 s[8:9], vcc
	s_cbranch_execz .LBB0_887
	s_mov_b32 s18, 1
	s_mov_b64 s[12:13], 0
	s_branch .LBB0_878

.LBB0_906:
	s_getpc_b64 s[98:99]
